# LRU tile loop: next tile x_b rows prefetched one tile ahead
# speedup vs baseline: 1.0141x; 1.0015x over previous
.LBB0_1092:
	s_or_b64 exec, exec, s[0:1]
	v_readlane_b32 s0, v254, 47
	v_and_b32_e32 v85, 7, v56
	v_readlane_b32 s9, v254, 53
	v_readlane_b32 s1, v254, 48
	v_mul_f32_e32 v124, 0xc1000000, v53
	v_lshl_or_b32 v84, v85, 3, s9
	v_lshl_add_u64 v[32:33], v[46:47], 0, s[0:1]
	v_lshlrev_b32_e32 v112, 2, v84
	v_lshl_add_u64 v[40:41], v[32:33], 0, v[112:113]
	v_add_co_u32_e32 v44, vcc, s16, v40
	v_readlane_b32 s0, v254, 49
	s_nop 0
	v_addc_co_u32_e32 v45, vcc, 0, v41, vcc
	v_add_co_u32_e32 v46, vcc, s75, v40
	v_readlane_b32 s1, v254, 50
	s_nop 0
	v_addc_co_u32_e32 v47, vcc, 0, v41, vcc
	v_add_co_u32_e32 v42, vcc, s74, v40
	v_lshl_add_u64 v[48:49], s[0:1], 2, v[48:49]
	s_nop 0
	v_addc_co_u32_e32 v43, vcc, 0, v41, vcc
	flat_load_dwordx4 v[68:71], v[40:41] offset:16
	flat_load_dwordx4 v[72:75], v[44:45] offset:16
	flat_load_dwordx4 v[32:35], v[46:47] offset:16
	flat_load_dwordx4 v[36:39], v[42:43] offset:16
	flat_load_dwordx4 v[76:79], v[40:41]
	s_nop 0
	flat_load_dwordx4 v[40:43], v[42:43]
	s_nop 0
	flat_load_dwordx4 v[80:83], v[44:45]
	s_nop 0
	flat_load_dwordx4 v[44:47], v[46:47]
	v_mul_f32_e32 v125, 0xc1000000, v52
	v_lshl_add_u64 v[52:53], v[48:49], 0, v[112:113]
	v_mul_f32_e32 v122, 0xc1000000, v55
	v_mul_f32_e32 v123, 0xc1000000, v54
	v_mul_f32_e32 v126, 0xc1000000, v51
	v_mul_f32_e32 v127, 0xc1000000, v50
	flat_load_dwordx4 v[48:51], v[52:53]
	s_nop 0
	flat_load_dwordx4 v[52:55], v[52:53] offset:16
	v_mul_f32_e32 v120, 0xc1000000, v59
	s_ashr_i32 s10, s2, 6
	v_lshlrev_b32_e32 v59, 2, v88
	s_add_i32 s0, 0, 0x1b000
	v_mul_f32_e32 v121, 0xc1000000, v58
	v_and_b32_e32 v58, 15, v56
	v_add_u32_e32 v129, s0, v59
	s_lshl_b32 s0, s10, 4
	v_mul_f32_e32 v117, 0xc1000000, v62
	v_or_b32_e32 v62, s0, v58
	s_movk_i32 s3, 0x90
	v_mul_f32_e32 v116, 0xc1000000, v63
	v_mul_lo_u32 v63, v62, s3
	s_movk_i32 s1, 0x110
	s_and_b32 s2, s2, 0x3fffffc0
	v_mul_f32_e32 v119, 0xc1000000, v60
	v_ashrrev_i32_e32 v60, 2, v56
	v_and_b32_e32 v131, 48, v56
	v_add_u32_e32 v132, 0, v63
	v_mul_lo_u32 v56, v62, s1
	s_ashr_i32 s1, s0, 31
	v_or_b32_e32 v63, s2, v88
	s_add_i32 s2, 0, 0x1a000
	v_mul_f32_e32 v114, 0xc1000000, v65
	v_readlane_b32 s4, v254, 17
	s_cmp_gt_i32 s10, 0
	v_or_b32_e32 v65, 16, v57
	v_mul_f32_e32 v89, 0xc1000000, v66
	v_mul_f32_e32 v115, 0xc1000000, v64
	s_waitcnt lgkmcnt(0)
	s_barrier
	v_and_b32_e32 v130, -2, v60
	v_lshl_add_u32 v133, v62, 7, v132
	v_add_u32_e32 v134, s4, v56
	v_add_u32_e32 v62, s4, v59
	v_lshlrev_b32_e32 v63, 2, v63
	v_readlane_b32 s8, v254, 18
	s_cselect_b64 s[4:5], -1, 0
	s_cmp_eq_u32 s10, 7
	v_or_b32_e32 v60, 1, v60
	v_lshlrev_b32_e32 v64, 1, v57
	v_lshlrev_b32_e32 v137, 2, v57
	v_lshlrev_b32_e32 v66, 1, v65
	v_lshlrev_b32_e32 v138, 2, v65
	v_or_b32_e32 v65, 32, v57
	v_or_b32_e32 v57, 48, v57
	v_mul_f32_e32 v118, 0xc1000000, v61
	v_mul_f32_e32 v128, 0xc1000000, v67
	v_lshl_add_u32 v61, v85, 4, 0
	v_add_u32_e32 v56, 0, v59
	v_add_u32_e32 v135, s2, v63
	v_add_u32_e32 v136, s8, v63
	s_cselect_b64 s[6:7], -1, 0
	s_mul_i32 s2, s10, 0x1100
	v_mul_lo_u32 v63, v130, s3
	v_mul_lo_u32 v60, v60, s3
	v_mad_u32_u24 v58, v58, s3, 0
	v_lshlrev_b32_e32 v67, 1, v65
	v_lshlrev_b32_e32 v139, 2, v65
	v_lshlrev_b32_e32 v65, 1, v57
	s_add_u32 s12, s20, s0
	s_mov_b32 s11, 0
	v_lshlrev_b32_e32 v140, 2, v57
	s_addc_u32 s13, s21, s1
	v_add_u32_e32 v141, s8, v59
	v_lshlrev_b32_e32 v106, 1, v84
	v_add_u32_e32 v142, v61, v63
	s_mov_b32 s98, 0
	v_add_u32_e32 v172, s98, v130
	v_add_u32_e32 v173, 0x7a01c00, v106
	v_add_u32_e32 v174, -3, v172
	v_max_i32_e32 v174, 0, v174
	v_add_u32_e32 v174, s20, v174
	v_mad_u32_u24 v174, v174, s33, v173
	global_load_dwordx4 v[228:231], v174, s[22:23]
	v_add_u32_e32 v175, -2, v172
	v_max_i32_e32 v175, 0, v175
	v_add_u32_e32 v175, s20, v175
	v_mad_u32_u24 v175, v175, s33, v173
	global_load_dwordx4 v[232:235], v175, s[22:23]
	v_add_u32_e32 v176, 1, v172
	v_max_i32_e32 v176, 0, v176
	v_add_u32_e32 v176, s20, v176
	v_mad_u32_u24 v176, v176, s33, v173
	global_load_dwordx4 v[236:239], v176, s[22:23]
	v_add_u32_e32 v177, -1, v172
	v_max_i32_e32 v177, 0, v177
	v_add_u32_e32 v177, s20, v177
	v_mad_u32_u24 v177, v177, s33, v173
	global_load_dwordx4 v[240:243], v177, s[22:23]
	v_add_u32_e32 v178, 0, v172
	v_max_i32_e32 v178, 0, v178
	v_add_u32_e32 v178, s20, v178
	v_mad_u32_u24 v178, v178, s33, v173
	global_load_dwordx4 v[244:247], v178, s[22:23]
	s_waitcnt vmcnt(0) lgkmcnt(0)
	v_mov_b32_e32 v93, v38
	v_mov_b32_e32 v92, v70
	v_mov_b32_e32 v90, v74
	v_mov_b32_e32 v91, v34
	v_mov_b32_e32 v34, v75
	v_mov_b32_e32 v38, v71
	v_mov_b32_e32 v94, v72
	v_mov_b32_e32 v95, v32
	v_mov_b32_e32 v32, v73
	v_mov_b32_e32 v96, v68
	v_mov_b32_e32 v97, v36
	v_mov_b32_e32 v36, v69
	v_mov_b32_e32 v98, v82
	v_mov_b32_e32 v99, v46
	v_mov_b32_e32 v46, v83
	v_mov_b32_e32 v100, v78
	v_mov_b32_e32 v101, v42
	v_mov_b32_e32 v42, v79
	v_mov_b32_e32 v102, v80
	v_mov_b32_e32 v103, v44
	v_mov_b32_e32 v44, v81
	v_mov_b32_e32 v104, v76
	v_mov_b32_e32 v105, v40
	v_mov_b32_e32 v40, v77
	v_add_u32_e32 v143, v61, v60
	v_add_u32_e32 v144, v58, v131
	v_add_u32_e32 v145, v132, v64
	v_add_u32_e32 v146, v132, v66
	v_add_u32_e32 v147, v132, v67
	v_add_u32_e32 v148, v132, v65
	s_lshl_b32 s14, s9, 1
	v_lshlrev_b32_e32 v108, 1, v88
	v_add_u32_e32 v149, s2, v56
	v_add_u32_e32 v150, s2, v62
	s_branch .LBB0_1094

.LBB0_1094:
	s_lshl_b32 s15, s11, 7
	s_mov_b64 s[0:1], s[22:23]
	v_add_u32_e32 v82, s15, v130
	s_add_u32 s8, s0, 0x7a00000
	v_max_i32_e32 v56, 3, v82
	s_addc_u32 s9, s1, 0
	v_add_u32_e32 v112, -3, v56
	v_lshl_add_u64 v[56:57], s[20:21], 0, v[112:113]
	v_mov_b64_e32 v[72:73], s[8:9]
	v_mad_u64_u32 v[58:59], s[0:1], v56, s33, v[72:73]
	v_mad_i32_i24 v59, v57, s33, v59
	v_mov_b32_e32 v107, v113
	v_lshl_add_u64 v[56:57], v[58:59], 0, v[106:107]
	v_add_co_u32_e32 v56, vcc, s74, v56
	v_max_i32_e32 v74, -1, v82
	s_nop 0
	v_addc_co_u32_e32 v57, vcc, 0, v57, vcc
	s_waitcnt vmcnt(16)
	v_mov_b32_e32 v64, v228
	v_mov_b32_e32 v65, v229
	v_mov_b32_e32 v66, v230
	v_mov_b32_e32 v67, v231
	v_or_b32_e32 v56, 1, v82
	v_max_i32_e32 v56, 3, v56
	v_add_u32_e32 v112, -3, v56
	v_lshl_add_u64 v[56:57], s[20:21], 0, v[112:113]
	v_mad_u64_u32 v[58:59], s[0:1], v56, s33, v[72:73]
	v_mad_i32_i24 v59, v57, s33, v59
	v_lshl_add_u64 v[56:57], v[58:59], 0, v[106:107]
	v_add_co_u32_e32 v56, vcc, s74, v56
	v_cmp_lt_i32_e64 s[2:3], 2, v82
	s_nop 0
	v_addc_co_u32_e32 v57, vcc, 0, v57, vcc
	v_mov_b32_e32 v68, v232
	v_mov_b32_e32 v69, v233
	v_mov_b32_e32 v70, v234
	v_mov_b32_e32 v71, v235
	v_max_i32_e32 v56, 1, v82
	v_add_u32_e32 v112, -1, v56
	v_lshl_add_u64 v[56:57], s[20:21], 0, v[112:113]
	v_max_i32_e32 v112, 0, v82
	v_lshl_add_u64 v[60:61], s[20:21], 0, v[112:113]
	v_add_u32_e32 v112, 1, v74
	v_lshl_add_u64 v[74:75], s[20:21], 0, v[112:113]
	v_mad_u64_u32 v[58:59], s[0:1], v56, s33, v[72:73]
	v_mad_u64_u32 v[62:63], s[0:1], v60, s33, v[72:73]
	v_mad_u64_u32 v[72:73], s[0:1], v74, s33, v[72:73]
	v_mad_i32_i24 v73, v75, s33, v73
	v_lshl_add_u64 v[72:73], v[72:73], 0, v[106:107]
	v_add_co_u32_e64 v72, s[0:1], s74, v72
	v_mad_i32_i24 v59, v57, s33, v59
	s_nop 0
	v_addc_co_u32_e64 v73, s[0:1], 0, v73, s[0:1]
	v_mov_b32_e32 v72, v236
	v_mov_b32_e32 v73, v237
	v_mov_b32_e32 v74, v238
	v_mov_b32_e32 v75, v239
	v_lshl_add_u64 v[56:57], v[58:59], 0, v[106:107]
	v_add_co_u32_e32 v56, vcc, s74, v56
	v_mad_i32_i24 v63, v61, s33, v63
	s_nop 0
	v_addc_co_u32_e32 v57, vcc, 0, v57, vcc
	v_lshl_add_u64 v[60:61], v[62:63], 0, v[106:107]
	v_add_co_u32_e32 v60, vcc, s74, v60
	v_mov_b32_e32 v56, v240
	v_mov_b32_e32 v57, v241
	v_mov_b32_e32 v58, v242
	v_mov_b32_e32 v59, v243
	s_nop 0
	v_addc_co_u32_e32 v61, vcc, 0, v61, vcc
	v_mov_b32_e32 v60, v244
	v_mov_b32_e32 v61, v245
	v_mov_b32_e32 v62, v246
	v_mov_b32_e32 v63, v247
	v_cmp_lt_i32_e32 vcc, -2, v82
	v_cmp_lt_i32_e64 s[0:1], -1, v82
	s_nop 0
	v_cndmask_b32_e64 v83, 0, v67, s[2:3]
	v_cndmask_b32_e64 v64, 0, v64, s[2:3]
	s_nop 0
	v_cndmask_b32_e32 v107, 0, v72, vcc
	v_cndmask_b32_e32 v109, 0, v73, vcc
	v_cndmask_b32_e32 v112, 0, v74, vcc
	v_cndmask_b32_e32 v151, 0, v75, vcc
	v_cmp_lt_i32_e32 vcc, 1, v82
	v_lshlrev_b32_e32 v74, 16, v64
	v_lshlrev_b32_e32 v72, 16, v83
	v_cndmask_b32_e32 v67, 0, v68, vcc
	v_lshlrev_b32_e32 v75, 16, v67
	v_pk_mul_f32 v[76:77], v[104:105], v[74:75]
	v_cndmask_b32_e32 v84, 0, v71, vcc
	v_add_f32_e32 v68, v48, v76
	v_add_f32_e32 v74, v68, v77
	v_and_b32_e32 v77, 0xffff0000, v67
	v_and_b32_e32 v76, 0xffff0000, v64
	v_pk_mul_f32 v[80:81], v[40:41], v[76:77]
	v_cndmask_b32_e64 v67, 0, v65, s[2:3]
	v_add_f32_e32 v64, v49, v80
	v_cndmask_b32_e32 v71, 0, v69, vcc
	v_add_f32_e32 v152, v64, v81
	v_lshlrev_b32_e32 v65, 16, v71
	v_lshlrev_b32_e32 v64, 16, v67
	v_pk_mul_f32 v[68:69], v[100:101], v[64:65]
	v_lshlrev_b32_e32 v73, 16, v84
	v_add_f32_e32 v64, v50, v68
	v_add_f32_e32 v64, v64, v69
	v_and_b32_e32 v69, 0xffff0000, v71
	v_and_b32_e32 v68, 0xffff0000, v67
	v_pk_mul_f32 v[78:79], v[92:93], v[72:73]
	v_pk_mul_f32 v[80:81], v[42:43], v[68:69]
	v_add_f32_e32 v72, v54, v78
	v_add_f32_e32 v67, v51, v80
	v_cndmask_b32_e64 v78, 0, v66, s[2:3]
	v_cndmask_b32_e32 v80, 0, v70, vcc
	v_add_f32_e32 v153, v67, v81
	v_lshlrev_b32_e32 v67, 16, v80
	v_lshlrev_b32_e32 v66, 16, v78
	v_pk_mul_f32 v[70:71], v[96:97], v[66:67]
	v_cmp_lt_i32_e32 vcc, 0, v82
	v_add_f32_e32 v66, v52, v70
	v_add_f32_e32 v66, v66, v71
	v_and_b32_e32 v71, 0xffff0000, v80
	v_and_b32_e32 v70, 0xffff0000, v78
	v_pk_mul_f32 v[80:81], v[36:37], v[70:71]
	v_add_f32_e32 v72, v72, v79
	v_add_f32_e32 v78, v53, v80
	v_add_f32_e32 v154, v78, v81
	v_and_b32_e32 v79, 0xffff0000, v84
	v_and_b32_e32 v78, 0xffff0000, v83
	s_nop 0
	v_cndmask_b32_e64 v60, 0, v60, s[0:1]
	v_cndmask_b32_e32 v56, 0, v56, vcc
	v_pk_mul_f32 v[80:81], v[38:39], v[78:79]
	v_lshlrev_b32_e32 v84, 16, v56
	v_lshlrev_b32_e32 v85, 16, v60
	v_add_f32_e32 v80, v55, v80
	v_cndmask_b32_e64 v156, 0, v63, s[0:1]
	v_cndmask_b32_e32 v59, 0, v59, vcc
	v_pk_mul_f32 v[86:87], v[102:103], v[84:85]
	v_add_f32_e32 v155, v80, v81
	v_lshlrev_b32_e32 v80, 16, v59
	v_lshlrev_b32_e32 v81, 16, v156
	v_add_f32_e32 v63, v74, v86
	v_pk_mul_f32 v[82:83], v[90:91], v[80:81]
	v_add_f32_e32 v74, v63, v87
	v_and_b32_e32 v87, 0xffff0000, v60
	v_and_b32_e32 v86, 0xffff0000, v56
	v_add_f32_e32 v72, v72, v82
	v_pk_mul_f32 v[110:111], v[44:45], v[86:87]
	v_cndmask_b32_e64 v63, 0, v61, s[0:1]
	v_cndmask_b32_e32 v82, 0, v57, vcc
	v_add_f32_e32 v56, v152, v110
	v_lshlrev_b32_e32 v60, 16, v82
	v_lshlrev_b32_e32 v61, 16, v63
	v_add_f32_e32 v157, v56, v111
	v_pk_mul_f32 v[56:57], v[98:99], v[60:61]
	v_and_b32_e32 v111, 0xffff0000, v63
	v_add_f32_e32 v56, v64, v56
	v_and_b32_e32 v110, 0xffff0000, v82
	v_add_f32_e32 v64, v56, v57
	v_pk_mul_f32 v[56:57], v[46:47], v[110:111]
	v_cndmask_b32_e64 v82, 0, v62, s[0:1]
	v_cndmask_b32_e32 v58, 0, v58, vcc
	v_add_f32_e32 v56, v153, v56
	v_lshlrev_b32_e32 v62, 16, v58
	v_lshlrev_b32_e32 v63, 16, v82
	v_add_f32_e32 v158, v56, v57
	v_pk_mul_f32 v[56:57], v[94:95], v[62:63]
	v_and_b32_e32 v153, 0xffff0000, v82
	v_add_f32_e32 v56, v66, v56
	v_and_b32_e32 v152, 0xffff0000, v58
	v_add_f32_e32 v66, v56, v57
	v_pk_mul_f32 v[56:57], v[32:33], v[152:153]
	v_add_f32_e32 v72, v72, v83
	v_add_f32_e32 v56, v154, v56
	v_and_b32_e32 v83, 0xffff0000, v156
	v_and_b32_e32 v82, 0xffff0000, v59
	v_add_f32_e32 v58, v56, v57
	v_pk_mul_f32 v[56:57], v[34:35], v[82:83]
	s_add_u32 s0, s12, s15
	v_add_f32_e32 v56, v155, v56
	v_add_f32_e32 v59, v56, v57
	v_cvt_pk_bf16_f32 v56, v74, v157
	v_cvt_pk_bf16_f32 v57, v64, v158
	v_cvt_pk_bf16_f32 v58, v66, v58
	v_cvt_pk_bf16_f32 v59, v72, v59
	ds_write_b128 v142, v[56:59] offset:18432
	v_pk_mov_b32 v[56:57], v[74:75], v[84:85] op_sel:[1,0]
	v_and_b32_e32 v59, 0xffff0000, v107
	v_pk_mul_f32 v[56:57], v[104:105], v[56:57]
	v_and_b32_e32 v75, 0xffff0000, v151
	v_add_f32_e32 v56, v48, v56
	v_add_f32_e32 v58, v56, v57
	v_pk_mov_b32 v[56:57], v[76:77], v[86:87] op_sel:[1,0]
	s_addc_u32 s1, s13, 0
	v_pk_mul_f32 v[56:57], v[40:41], v[56:57]
	s_mulk_i32 s1, 0x2400
	v_add_f32_e32 v56, v49, v56
	v_add_f32_e32 v64, v56, v57
	v_pk_mov_b32 v[56:57], v[64:65], v[60:61] op_sel:[1,0]
	v_lshlrev_b32_e32 v65, 16, v109
	v_pk_mul_f32 v[56:57], v[100:101], v[56:57]
	s_mul_hi_u32 s2, s0, 0x2400
	v_add_f32_e32 v56, v50, v56
	v_add_f32_e32 v60, v56, v57
	v_pk_mov_b32 v[56:57], v[68:69], v[110:111] op_sel:[1,0]
	v_lshlrev_b32_e32 v69, 16, v112
	v_pk_mul_f32 v[56:57], v[42:43], v[56:57]
	s_add_i32 s2, s2, s1
	v_add_f32_e32 v56, v51, v56
	v_add_f32_e32 v68, v56, v57
	v_pk_mov_b32 v[56:57], v[66:67], v[62:63] op_sel:[1,0]
	v_and_b32_e32 v67, 0xffff0000, v109
	v_pk_mul_f32 v[56:57], v[96:97], v[56:57]
	v_mov_b32_e32 v66, v111
	v_add_f32_e32 v56, v52, v56
	v_add_f32_e32 v62, v56, v57
	v_pk_mov_b32 v[56:57], v[70:71], v[152:153] op_sel:[1,0]
	v_and_b32_e32 v71, 0xffff0000, v112
	v_pk_mul_f32 v[56:57], v[36:37], v[56:57]
	v_mov_b32_e32 v70, v153
	v_add_f32_e32 v56, v53, v56
	v_add_f32_e32 v72, v56, v57
	v_pk_mov_b32 v[56:57], v[72:73], v[80:81] op_sel:[1,0]
	v_lshlrev_b32_e32 v73, 16, v151
	v_pk_mul_f32 v[56:57], v[92:93], v[56:57]
	v_add_u32_e32 v80, v132, v131
	v_add_f32_e32 v56, v54, v56
	v_add_f32_e32 v74, v56, v57
	v_pk_mov_b32 v[56:57], v[78:79], v[82:83] op_sel:[1,0]
	s_mulk_i32 s0, 0x2400
	v_pk_mul_f32 v[56:57], v[38:39], v[56:57]
	s_add_u32 s0, s8, s0
	v_add_f32_e32 v56, v55, v56
	v_add_f32_e32 v76, v56, v57
	v_lshlrev_b32_e32 v57, 16, v107
	v_mov_b32_e32 v56, v85
	v_pk_mul_f32 v[56:57], v[102:103], v[56:57]
	s_addc_u32 s1, s9, s2
	v_add_f32_e32 v56, v58, v56
	v_mov_b32_e32 v58, v87
	v_add_f32_e32 v77, v56, v57
	v_pk_mul_f32 v[56:57], v[44:45], v[58:59]
	s_add_u32 s0, s0, s14
	v_add_f32_e32 v56, v64, v56
	v_mov_b32_e32 v64, v61
	v_add_f32_e32 v58, v56, v57
	v_pk_mul_f32 v[56:57], v[98:99], v[64:65]
	s_addc_u32 s1, s1, 0
	v_add_f32_e32 v56, v60, v56
	v_add_f32_e32 v59, v56, v57
	v_pk_mul_f32 v[56:57], v[46:47], v[66:67]
	v_mov_b32_e32 v109, v113
	v_add_f32_e32 v56, v68, v56
	v_mov_b32_e32 v68, v63
	v_add_f32_e32 v60, v56, v57
	v_pk_mul_f32 v[56:57], v[94:95], v[68:69]
	s_nop 0
	v_add_f32_e32 v56, v62, v56
	v_add_f32_e32 v61, v56, v57
	v_pk_mul_f32 v[56:57], v[32:33], v[70:71]
	s_nop 0
	v_add_f32_e32 v56, v72, v56
	v_mov_b32_e32 v72, v81
	v_add_f32_e32 v62, v56, v57
	v_pk_mul_f32 v[56:57], v[90:91], v[72:73]
	s_nop 0
	v_add_f32_e32 v56, v74, v56
	v_mov_b32_e32 v74, v83
	v_add_f32_e32 v63, v56, v57
	v_pk_mul_f32 v[56:57], v[34:35], v[74:75]
	s_nop 0
	v_add_f32_e32 v56, v76, v56
	v_add_f32_e32 v64, v56, v57
	v_cvt_pk_bf16_f32 v56, v77, v58
	v_cvt_pk_bf16_f32 v57, v59, v60
	v_cvt_pk_bf16_f32 v58, v61, v62
	v_cvt_pk_bf16_f32 v59, v63, v64
	ds_write_b128 v143, v[56:59] offset:18432
	s_waitcnt lgkmcnt(0)
	s_barrier
	s_add_i32 s98, s11, 1
	s_min_u32 s98, s98, 15
	s_lshl_b32 s98, s98, 7
	v_add_u32_e32 v172, s98, v130
	v_add_u32_e32 v173, 0x7a01c00, v106
	v_add_u32_e32 v174, -3, v172
	v_max_i32_e32 v174, 0, v174
	v_add_u32_e32 v174, s20, v174
	v_mad_u32_u24 v174, v174, s33, v173
	global_load_dwordx4 v[228:231], v174, s[22:23]
	v_add_u32_e32 v175, -2, v172
	v_max_i32_e32 v175, 0, v175
	v_add_u32_e32 v175, s20, v175
	v_mad_u32_u24 v175, v175, s33, v173
	global_load_dwordx4 v[232:235], v175, s[22:23]
	v_add_u32_e32 v176, 1, v172
	v_max_i32_e32 v176, 0, v176
	v_add_u32_e32 v176, s20, v176
	v_mad_u32_u24 v176, v176, s33, v173
	global_load_dwordx4 v[236:239], v176, s[22:23]
	v_add_u32_e32 v177, -1, v172
	v_max_i32_e32 v177, 0, v177
	v_add_u32_e32 v177, s20, v177
	v_mad_u32_u24 v177, v177, s33, v173
	global_load_dwordx4 v[240:243], v177, s[22:23]
	v_add_u32_e32 v178, 0, v172
	v_max_i32_e32 v178, 0, v178
	v_add_u32_e32 v178, s20, v178
	v_mad_u32_u24 v178, v178, s33, v173
	global_load_dwordx4 v[244:247], v178, s[22:23]
	ds_read_b128 v[56:59], v80 offset:18432
	ds_read_b128 v[60:63], v144
	ds_read_b128 v[68:71], v144 offset:2304
	ds_read_b128 v[76:79], v144 offset:4608
	ds_read_b128 v[72:75], v144 offset:11520
	s_waitcnt lgkmcnt(1)
	v_mfma_f32_16x16x32_bf16 v[152:155], v[76:79], v[56:59], 0
	ds_read_b128 v[76:79], v144 offset:13824
	ds_read_b128 v[64:67], v144 offset:9216
	s_waitcnt lgkmcnt(1)
	v_mfma_f32_16x16x32_bf16 v[156:159], v[76:79], v[56:59], 0
	ds_read_b128 v[76:79], v144 offset:6912
	s_waitcnt lgkmcnt(0)
	v_mfma_f32_16x16x32_bf16 v[160:163], v[76:79], v[56:59], 0
	ds_read_b128 v[76:79], v144 offset:16128
	v_mfma_f32_16x16x32_bf16 v[60:63], v[60:63], v[56:59], 0
	v_mfma_f32_16x16x32_bf16 v[64:67], v[64:67], v[56:59], 0
	v_mfma_f32_16x16x32_bf16 v[68:71], v[68:71], v[56:59], 0
	v_mfma_f32_16x16x32_bf16 v[72:75], v[72:75], v[56:59], 0
	s_waitcnt lgkmcnt(0)
	v_mfma_f32_16x16x32_bf16 v[164:167], v[76:79], v[56:59], 0
	ds_read_b128 v[168:171], v80 offset:18496
	ds_read_b128 v[56:59], v144 offset:64
	ds_read_b64 v[110:111], v145 offset:18432
	s_waitcnt lgkmcnt(1)
	v_mfma_f32_16x16x32_bf16 v[84:87], v[56:59], v[168:171], v[60:63]
	ds_read_b128 v[56:59], v144 offset:9280
	s_nop 1
	ds_read_b128 v[60:63], v144 offset:16192
	s_waitcnt lgkmcnt(1)
	v_mfma_f32_16x16x32_bf16 v[80:83], v[56:59], v[168:171], v[64:67]
	ds_read_b128 v[56:59], v144 offset:2368
	s_nop 0
	v_add_f32_e32 v84, v0, v84
	v_mul_f32_e32 v84, 0xbfb8aa3b, v84
	s_waitcnt lgkmcnt(0)
	v_mfma_f32_16x16x32_bf16 v[76:79], v[56:59], v[168:171], v[68:71]
	ds_read_b128 v[56:59], v144 offset:11584
	v_exp_f32_e32 v84, v84
	v_add_f32_e32 v80, v4, v80
	v_mul_f32_e32 v80, 0xbfb8aa3b, v80
	v_exp_f32_e32 v80, v80
	v_add_f32_e32 v84, 1.0, v84
	v_rcp_f32_e32 v107, v84
	s_waitcnt lgkmcnt(0)
	v_mfma_f32_16x16x32_bf16 v[72:75], v[56:59], v[168:171], v[72:75]
	ds_read_b128 v[56:59], v144 offset:4672
	v_add_f32_e32 v80, 1.0, v80
	v_mul_f32_e32 v107, v127, v107
	v_rcp_f32_e32 v84, v80
	v_mul_f32_e32 v80, 0x3fb8aa3b, v107
	v_add_f32_e32 v107, v107, v107
	v_mul_f32_e32 v107, 0x3fb8aa3b, v107
	v_add_f32_e32 v85, v1, v85
	v_exp_f32_e32 v107, v107
	v_mul_f32_e32 v85, 0xbfb8aa3b, v85
	v_exp_f32_e32 v85, v85
	v_add_f32_e32 v81, v5, v81
	v_sub_f32_e32 v107, 1.0, v107
	v_max_f32_e32 v107, 0, v107
	v_add_f32_e32 v85, 1.0, v85
	v_mul_f32_e32 v81, 0xbfb8aa3b, v81
	s_waitcnt lgkmcnt(0)
	v_mfma_f32_16x16x32_bf16 v[68:71], v[56:59], v[168:171], v[152:155]
	v_exp_f32_e32 v81, v81
	v_add_f32_e32 v86, v2, v86
	v_mul_f32_e32 v86, 0xbfb8aa3b, v86
	v_sqrt_f32_e32 v152, v107
	v_rcp_f32_e32 v107, v85
	v_add_f32_e32 v81, 1.0, v81
	v_rcp_f32_e32 v85, v81
	v_exp_f32_e32 v86, v86
	v_mul_f32_e32 v107, v126, v107
	v_mul_f32_e32 v81, 0x3fb8aa3b, v107
	v_add_f32_e32 v107, v107, v107
	v_mul_f32_e32 v107, 0x3fb8aa3b, v107
	v_exp_f32_e32 v107, v107
	v_add_f32_e32 v82, v6, v82
	v_add_f32_e32 v86, 1.0, v86
	v_mul_f32_e32 v82, 0xbfb8aa3b, v82
	v_sub_f32_e32 v107, 1.0, v107
	v_max_f32_e32 v107, 0, v107
	v_sqrt_f32_e32 v153, v107
	v_rcp_f32_e32 v107, v86
	v_exp_f32_e32 v82, v82
	v_add_f32_e32 v87, v3, v87
	v_mul_f32_e32 v87, 0xbfb8aa3b, v87
	v_mul_f32_e32 v107, v125, v107
	v_add_f32_e32 v82, 1.0, v82
	v_rcp_f32_e32 v86, v82
	v_mul_f32_e32 v82, 0x3fb8aa3b, v107
	v_add_f32_e32 v107, v107, v107
	v_mul_f32_e32 v107, 0x3fb8aa3b, v107
	v_exp_f32_e32 v107, v107
	v_exp_f32_e32 v87, v87
	v_add_f32_e32 v83, v7, v83
	v_mul_f32_e32 v83, 0xbfb8aa3b, v83
	v_sub_f32_e32 v107, 1.0, v107
	v_max_f32_e32 v107, 0, v107
	v_add_f32_e32 v87, 1.0, v87
	v_pk_mul_f32 v[84:85], v[84:85], v[152:153]
	v_sqrt_f32_e32 v152, v107
	v_rcp_f32_e32 v107, v87
	v_exp_f32_e32 v83, v83
	ds_read_b128 v[56:59], v144 offset:13888
	v_exp_f32_e32 v80, v80
	v_mul_f32_e32 v107, v124, v107
	v_add_f32_e32 v83, 1.0, v83
	v_rcp_f32_e32 v87, v83
	v_mul_f32_e32 v83, 0x3fb8aa3b, v107
	v_add_f32_e32 v107, v107, v107
	v_mul_f32_e32 v107, 0x3fb8aa3b, v107
	v_exp_f32_e32 v107, v107
	v_exp_f32_e32 v81, v81
	v_exp_f32_e32 v82, v82
	v_exp_f32_e32 v83, v83
	v_sub_f32_e32 v107, 1.0, v107
	v_max_f32_e32 v107, 0, v107
	v_sqrt_f32_e32 v153, v107
	v_add_f32_e32 v76, v8, v76
	v_add_f32_e32 v77, v9, v77
	v_mul_f32_e32 v76, 0xbfb8aa3b, v76
	v_mul_f32_e32 v77, 0xbfb8aa3b, v77
	v_exp_f32_e32 v76, v76
	v_exp_f32_e32 v77, v77
	v_lshlrev_b32_e32 v154, 16, v110
	v_and_b32_e32 v155, 0xffff0000, v110
	v_lshlrev_b32_e32 v110, 16, v111
	v_and_b32_e32 v111, 0xffff0000, v111
	v_pk_mul_f32 v[86:87], v[86:87], v[152:153]
	v_add_u32_e32 v107, v133, v137
	s_waitcnt lgkmcnt(0)
	v_mfma_f32_16x16x32_bf16 v[64:67], v[56:59], v[168:171], v[156:159]
	ds_read_b128 v[56:59], v144 offset:6976
	v_pk_mul_f32 v[84:85], v[84:85], v[154:155]
	v_pk_mul_f32 v[86:87], v[86:87], v[110:111]
	ds_write_b128 v107, v[80:83] offset:36864
	v_add_u32_e32 v80, v134, v137
	v_add_f32_e32 v78, v10, v78
	ds_write_b128 v80, v[84:87]
	v_add_f32_e32 v72, v12, v72
	v_add_f32_e32 v73, v13, v73
	v_mul_f32_e32 v78, 0xbfb8aa3b, v78
	ds_read_b64 v[80:81], v146 offset:18432
	v_add_f32_e32 v76, 1.0, v76
	v_mul_f32_e32 v72, 0xbfb8aa3b, v72
	v_add_f32_e32 v77, 1.0, v77
	v_mul_f32_e32 v73, 0xbfb8aa3b, v73
	v_exp_f32_e32 v78, v78
	v_rcp_f32_e32 v82, v76
	v_exp_f32_e32 v72, v72
	v_rcp_f32_e32 v83, v77
	v_exp_f32_e32 v73, v73
	v_add_f32_e32 v74, v14, v74
	v_add_f32_e32 v78, 1.0, v78
	v_mul_f32_e32 v74, 0xbfb8aa3b, v74
	v_add_f32_e32 v72, 1.0, v72
	v_mul_f32_e32 v82, v123, v82
	v_add_f32_e32 v73, 1.0, v73
	v_mul_f32_e32 v83, v122, v83
	s_waitcnt lgkmcnt(0)
	v_lshlrev_b32_e32 v84, 16, v80
	v_and_b32_e32 v85, 0xffff0000, v80
	v_rcp_f32_e32 v80, v78
	v_exp_f32_e32 v74, v74
	v_rcp_f32_e32 v76, v72
	v_mul_f32_e32 v72, 0x3fb8aa3b, v82
	v_add_f32_e32 v82, v82, v82
	v_rcp_f32_e32 v77, v73
	v_mul_f32_e32 v73, 0x3fb8aa3b, v83
	v_add_f32_e32 v83, v83, v83
	v_mul_f32_e32 v82, 0x3fb8aa3b, v82
	v_mul_f32_e32 v83, 0x3fb8aa3b, v83
	v_exp_f32_e32 v82, v82
	v_exp_f32_e32 v83, v83
	v_add_f32_e32 v74, 1.0, v74
	v_mul_f32_e32 v80, v121, v80
	v_rcp_f32_e32 v78, v74
	v_mul_f32_e32 v74, 0x3fb8aa3b, v80
	v_add_f32_e32 v80, v80, v80
	v_mul_f32_e32 v80, 0x3fb8aa3b, v80
	v_add_f32_e32 v79, v11, v79
	v_sub_f32_e32 v82, 1.0, v82
	v_sub_f32_e32 v83, 1.0, v83
	v_exp_f32_e32 v80, v80
	v_mul_f32_e32 v79, 0xbfb8aa3b, v79
	v_max_f32_e32 v82, 0, v82
	v_max_f32_e32 v83, 0, v83
	v_exp_f32_e32 v79, v79
	v_sqrt_f32_e32 v82, v82
	v_sqrt_f32_e32 v83, v83
	v_sub_f32_e32 v80, 1.0, v80
	v_add_f32_e32 v75, v15, v75
	v_max_f32_e32 v80, 0, v80
	v_add_f32_e32 v79, 1.0, v79
	v_mul_f32_e32 v75, 0xbfb8aa3b, v75
	v_pk_mul_f32 v[76:77], v[76:77], v[82:83]
	v_sqrt_f32_e32 v82, v80
	v_rcp_f32_e32 v80, v79
	v_exp_f32_e32 v75, v75
	v_exp_f32_e32 v72, v72
	v_exp_f32_e32 v73, v73
	v_mul_f32_e32 v80, v120, v80
	v_add_f32_e32 v75, 1.0, v75
	v_rcp_f32_e32 v79, v75
	v_mul_f32_e32 v75, 0x3fb8aa3b, v80
	v_add_f32_e32 v80, v80, v80
	v_mul_f32_e32 v80, 0x3fb8aa3b, v80
	v_exp_f32_e32 v80, v80
	v_exp_f32_e32 v74, v74
	v_exp_f32_e32 v75, v75
	v_add_f32_e32 v68, v16, v68
	v_sub_f32_e32 v80, 1.0, v80
	v_max_f32_e32 v80, 0, v80
	v_sqrt_f32_e32 v83, v80
	v_add_f32_e32 v69, v17, v69
	v_mul_f32_e32 v68, 0xbfb8aa3b, v68
	v_mul_f32_e32 v69, 0xbfb8aa3b, v69
	v_lshlrev_b32_e32 v80, 16, v81
	v_and_b32_e32 v81, 0xffff0000, v81
	v_pk_mul_f32 v[78:79], v[78:79], v[82:83]
	v_exp_f32_e32 v68, v68
	v_exp_f32_e32 v69, v69
	v_pk_mul_f32 v[78:79], v[78:79], v[80:81]
	v_add_u32_e32 v80, v133, v138
	v_pk_mul_f32 v[76:77], v[76:77], v[84:85]
	ds_write_b128 v80, v[72:75] offset:36864
	v_add_u32_e32 v72, v134, v138
	v_add_f32_e32 v70, v18, v70
	ds_write_b128 v72, v[76:79]
	v_add_f32_e32 v64, v20, v64
	v_add_f32_e32 v65, v21, v65
	v_mul_f32_e32 v70, 0xbfb8aa3b, v70
	ds_read_b64 v[72:73], v147 offset:18432
	v_add_f32_e32 v68, 1.0, v68
	v_mul_f32_e32 v64, 0xbfb8aa3b, v64
	v_add_f32_e32 v69, 1.0, v69
	v_mul_f32_e32 v65, 0xbfb8aa3b, v65
	v_exp_f32_e32 v70, v70
	v_rcp_f32_e32 v74, v68
	v_exp_f32_e32 v64, v64
	v_rcp_f32_e32 v75, v69
	v_exp_f32_e32 v65, v65
	v_add_f32_e32 v66, v22, v66
	v_add_f32_e32 v70, 1.0, v70
	v_mul_f32_e32 v66, 0xbfb8aa3b, v66
	v_add_f32_e32 v64, 1.0, v64
	v_mul_f32_e32 v74, v119, v74
	v_add_f32_e32 v65, 1.0, v65
	v_mul_f32_e32 v75, v118, v75
	s_waitcnt lgkmcnt(0)
	v_lshlrev_b32_e32 v76, 16, v72
	v_and_b32_e32 v77, 0xffff0000, v72
	v_rcp_f32_e32 v72, v70
	v_exp_f32_e32 v66, v66
	v_rcp_f32_e32 v68, v64
	v_mul_f32_e32 v64, 0x3fb8aa3b, v74
	v_add_f32_e32 v74, v74, v74
	v_rcp_f32_e32 v69, v65
	v_mul_f32_e32 v65, 0x3fb8aa3b, v75
	v_add_f32_e32 v75, v75, v75
	v_mul_f32_e32 v74, 0x3fb8aa3b, v74
	v_mul_f32_e32 v75, 0x3fb8aa3b, v75
	v_exp_f32_e32 v74, v74
	v_exp_f32_e32 v75, v75
	v_add_f32_e32 v66, 1.0, v66
	v_mul_f32_e32 v72, v117, v72
	v_rcp_f32_e32 v70, v66
	v_mul_f32_e32 v66, 0x3fb8aa3b, v72
	v_add_f32_e32 v72, v72, v72
	v_mul_f32_e32 v72, 0x3fb8aa3b, v72
	v_add_f32_e32 v71, v19, v71
	v_sub_f32_e32 v74, 1.0, v74
	v_sub_f32_e32 v75, 1.0, v75
	v_exp_f32_e32 v72, v72
	v_mul_f32_e32 v71, 0xbfb8aa3b, v71
	v_max_f32_e32 v74, 0, v74
	v_max_f32_e32 v75, 0, v75
	v_exp_f32_e32 v71, v71
	v_sqrt_f32_e32 v74, v74
	v_sqrt_f32_e32 v75, v75
	v_sub_f32_e32 v72, 1.0, v72
	v_add_f32_e32 v67, v23, v67
	v_max_f32_e32 v72, 0, v72
	v_add_f32_e32 v71, 1.0, v71
	v_mul_f32_e32 v67, 0xbfb8aa3b, v67
	v_pk_mul_f32 v[68:69], v[68:69], v[74:75]
	v_sqrt_f32_e32 v74, v72
	v_rcp_f32_e32 v72, v71
	v_exp_f32_e32 v67, v67
	v_mfma_f32_16x16x32_bf16 v[56:59], v[56:59], v[168:171], v[160:163]
	v_exp_f32_e32 v64, v64
	v_mul_f32_e32 v72, v116, v72
	v_add_f32_e32 v67, 1.0, v67
	v_rcp_f32_e32 v71, v67
	v_mul_f32_e32 v67, 0x3fb8aa3b, v72
	v_add_f32_e32 v72, v72, v72
	v_mul_f32_e32 v72, 0x3fb8aa3b, v72
	v_exp_f32_e32 v72, v72
	v_add_f32_e32 v56, v24, v56
	v_add_f32_e32 v57, v25, v57
	v_mul_f32_e32 v56, 0xbfb8aa3b, v56
	v_sub_f32_e32 v72, 1.0, v72
	v_max_f32_e32 v72, 0, v72
	v_mul_f32_e32 v57, 0xbfb8aa3b, v57
	v_sqrt_f32_e32 v75, v72
	v_exp_f32_e32 v56, v56
	v_exp_f32_e32 v57, v57
	v_exp_f32_e32 v65, v65
	v_exp_f32_e32 v66, v66
	v_exp_f32_e32 v67, v67
	v_add_f32_e32 v58, v26, v58
	v_mul_f32_e32 v58, 0xbfb8aa3b, v58
	v_lshlrev_b32_e32 v72, 16, v73
	v_and_b32_e32 v73, 0xffff0000, v73
	v_pk_mul_f32 v[70:71], v[70:71], v[74:75]
	v_add_f32_e32 v56, 1.0, v56
	v_add_f32_e32 v57, 1.0, v57
	v_exp_f32_e32 v58, v58
	v_pk_mul_f32 v[70:71], v[70:71], v[72:73]
	v_add_u32_e32 v72, v133, v139
	v_rcp_f32_e32 v56, v56
	v_rcp_f32_e32 v57, v57
	v_pk_mul_f32 v[68:69], v[68:69], v[76:77]
	ds_write_b128 v72, v[64:67] offset:36864
	v_add_u32_e32 v64, v134, v139
	v_mfma_f32_16x16x32_bf16 v[60:63], v[60:63], v[168:171], v[164:167]
	ds_write_b128 v64, v[68:71]
	ds_read_b64 v[64:65], v148 offset:18432
	v_add_f32_e32 v58, 1.0, v58
	v_mul_f32_e32 v66, v115, v56
	v_mul_f32_e32 v67, v114, v57
	v_rcp_f32_e32 v58, v58
	v_mul_f32_e32 v56, 0x3fb8aa3b, v66
	v_add_f32_e32 v66, v66, v66
	v_mul_f32_e32 v57, 0x3fb8aa3b, v67
	v_add_f32_e32 v67, v67, v67
	v_add_f32_e32 v60, v28, v60
	v_mul_f32_e32 v66, 0x3fb8aa3b, v66
	v_add_f32_e32 v61, v29, v61
	v_mul_f32_e32 v67, 0x3fb8aa3b, v67
	v_add_f32_e32 v59, v27, v59
	v_mul_f32_e32 v60, 0xbfb8aa3b, v60
	v_exp_f32_e32 v66, v66
	v_mul_f32_e32 v61, 0xbfb8aa3b, v61
	v_exp_f32_e32 v67, v67
	v_mul_f32_e32 v59, 0xbfb8aa3b, v59
	v_exp_f32_e32 v60, v60
	v_exp_f32_e32 v61, v61
	s_waitcnt lgkmcnt(0)
	v_lshlrev_b32_e32 v68, 16, v64
	v_and_b32_e32 v69, 0xffff0000, v64
	v_mul_f32_e32 v64, v89, v58
	v_exp_f32_e32 v59, v59
	v_mul_f32_e32 v58, 0x3fb8aa3b, v64
	v_add_f32_e32 v64, v64, v64
	v_mul_f32_e32 v64, 0x3fb8aa3b, v64
	v_sub_f32_e32 v66, 1.0, v66
	v_sub_f32_e32 v67, 1.0, v67
	v_exp_f32_e32 v64, v64
	v_add_f32_e32 v60, 1.0, v60
	v_max_f32_e32 v66, 0, v66
	v_add_f32_e32 v61, 1.0, v61
	v_max_f32_e32 v67, 0, v67
	v_add_f32_e32 v59, 1.0, v59
	v_rcp_f32_e32 v60, v60
	v_sqrt_f32_e32 v66, v66
	v_rcp_f32_e32 v61, v61
	v_sqrt_f32_e32 v67, v67
	v_rcp_f32_e32 v59, v59
	v_sub_f32_e32 v64, 1.0, v64
	v_max_f32_e32 v64, 0, v64
	v_pk_mul_f32 v[60:61], v[60:61], v[66:67]
	v_sqrt_f32_e32 v66, v64
	v_mul_f32_e32 v64, v128, v59
	v_mul_f32_e32 v59, 0x3fb8aa3b, v64
	v_add_f32_e32 v64, v64, v64
	v_add_f32_e32 v62, v30, v62
	v_add_f32_e32 v63, v31, v63
	v_mul_f32_e32 v64, 0x3fb8aa3b, v64
	v_mul_f32_e32 v62, 0xbfb8aa3b, v62
	v_mul_f32_e32 v63, 0xbfb8aa3b, v63
	v_exp_f32_e32 v64, v64
	v_exp_f32_e32 v62, v62
	v_exp_f32_e32 v63, v63
	v_exp_f32_e32 v56, v56
	v_sub_f32_e32 v64, 1.0, v64
	v_add_f32_e32 v62, 1.0, v62
	v_add_f32_e32 v63, 1.0, v63
	v_max_f32_e32 v64, 0, v64
	v_rcp_f32_e32 v62, v62
	v_rcp_f32_e32 v63, v63
	v_sqrt_f32_e32 v67, v64
	v_exp_f32_e32 v57, v57
	v_exp_f32_e32 v58, v58
	v_exp_f32_e32 v59, v59
	v_lshlrev_b32_e32 v64, 16, v65
	v_and_b32_e32 v65, 0xffff0000, v65
	v_pk_mul_f32 v[62:63], v[62:63], v[66:67]
	v_pk_mul_f32 v[60:61], v[60:61], v[68:69]
	v_pk_mul_f32 v[62:63], v[62:63], v[64:65]
	v_add_u32_e32 v64, v133, v140
	ds_write_b128 v64, v[56:59] offset:36864
	v_add_u32_e32 v56, v134, v140
	v_lshl_add_u64 v[66:67], s[0:1], 0, v[108:109]
	ds_write_b128 v56, v[60:63]
	v_add_co_u32_e32 v56, vcc, s16, v66
	s_waitcnt lgkmcnt(0)
	s_barrier
	s_nop 0
	v_addc_co_u32_e32 v57, vcc, 0, v67, vcc
	global_load_ushort v163, v108, s[0:1] offset:2048
	global_load_ushort v162, v[56:57], off offset:3072
	s_movk_i32 s0, 0x5000
	v_add_co_u32_e32 v56, vcc, s0, v66
	s_movk_i32 s0, 0x7000
	s_nop 0
	v_addc_co_u32_e32 v57, vcc, 0, v67, vcc
	global_load_ushort v161, v[56:57], off
	v_add_co_u32_e32 v56, vcc, s0, v66
	s_mov_b32 s0, 0x9000
	s_nop 0
	v_addc_co_u32_e32 v57, vcc, 0, v67, vcc
	global_load_ushort v160, v[56:57], off offset:1024
	v_add_co_u32_e32 v56, vcc, s0, v66
	s_mov_b32 s0, 0xb000
	s_nop 0
	v_addc_co_u32_e32 v57, vcc, 0, v67, vcc
	global_load_ushort v159, v[56:57], off offset:2048
	v_add_co_u32_e32 v56, vcc, s0, v66
	s_mov_b32 s0, 0xe000
	s_nop 0
	v_addc_co_u32_e32 v57, vcc, 0, v67, vcc
	global_load_ushort v158, v[56:57], off offset:3072
	v_add_co_u32_e32 v56, vcc, s0, v66
	s_mov_b32 s0, 0x10000
	s_nop 0
	v_addc_co_u32_e32 v57, vcc, 0, v67, vcc
	global_load_ushort v157, v[56:57], off
	v_add_co_u32_e32 v56, vcc, s0, v66
	s_mov_b32 s0, 0x12000
	s_nop 0
	v_addc_co_u32_e32 v57, vcc, 0, v67, vcc
	global_load_ushort v156, v[56:57], off offset:1024
	v_add_co_u32_e32 v56, vcc, s0, v66
	s_mov_b32 s0, 0x14000
	s_nop 0
	v_addc_co_u32_e32 v57, vcc, 0, v67, vcc
	global_load_ushort v155, v[56:57], off offset:2048
	v_add_co_u32_e32 v56, vcc, s0, v66
	s_mov_b32 s0, 0x17000
	s_nop 0
	v_addc_co_u32_e32 v57, vcc, 0, v67, vcc
	global_load_ushort v154, v[56:57], off offset:3072
	v_add_co_u32_e32 v56, vcc, s0, v66
	s_mov_b32 s0, 0x19000
	s_nop 0
	v_addc_co_u32_e32 v57, vcc, 0, v67, vcc
	global_load_ushort v153, v[56:57], off
	v_add_co_u32_e32 v56, vcc, s0, v66
	s_mov_b32 s0, 0x1b000
	s_nop 0
	v_addc_co_u32_e32 v57, vcc, 0, v67, vcc
	global_load_ushort v152, v[56:57], off offset:1024
	v_add_co_u32_e32 v56, vcc, s0, v66
	s_mov_b32 s0, 0x1d000
	s_nop 0
	v_addc_co_u32_e32 v57, vcc, 0, v67, vcc
	global_load_ushort v151, v[56:57], off offset:2048
	v_add_co_u32_e32 v56, vcc, s0, v66
	s_mov_b32 s0, 0x20000
	s_nop 0
	v_addc_co_u32_e32 v57, vcc, 0, v67, vcc
	global_load_ushort v112, v[56:57], off offset:3072
	v_add_co_u32_e32 v56, vcc, s0, v66
	s_mov_b32 s0, 0x22000
	s_nop 0
	v_addc_co_u32_e32 v57, vcc, 0, v67, vcc
	global_load_ushort v109, v[56:57], off
	v_add_co_u32_e32 v56, vcc, s0, v66
	v_add_u32_e32 v62, 0x9000, v149
	s_nop 0
	v_addc_co_u32_e32 v57, vcc, 0, v67, vcc
	global_load_ushort v107, v[56:57], off offset:1024
	ds_read2_b32 v[56:57], v62 offset1:68
	ds_read2_b32 v[58:59], v150 offset1:68
	s_lshl_b32 s0, s11, 6
	s_and_b32 s0, s0, 64
	s_andn2_b64 vcc, exec, s[4:5]
	s_waitcnt lgkmcnt(1)
	v_mul_f32_e32 v63, v56, v57
	s_waitcnt lgkmcnt(0)
	v_fma_f32 v58, 0, v56, v58
	v_fmac_f32_e32 v59, v58, v57
	ds_write2_b32 v150, v58, v59 offset1:68
	ds_read2_b32 v[56:57], v62 offset0:136 offset1:204
	ds_read2_b32 v[60:61], v150 offset0:136 offset1:204
	s_mov_b32 s1, s10
	s_waitcnt lgkmcnt(0)
	v_fma_f32 v58, v59, v56, v60
	v_mul_f32_e32 v56, v63, v56
	ds_write2_b32 v62, v63, v56 offset0:68 offset1:136
	v_fmac_f32_e32 v61, v58, v57
	v_add_u32_e32 v62, 0x9400, v149
	v_add_u32_e32 v63, 0x400, v150
	v_mul_f32_e32 v60, v56, v57
	ds_write2_b32 v150, v58, v61 offset0:136 offset1:204
	ds_read2_b32 v[56:57], v62 offset0:16 offset1:84
	ds_read2_b32 v[58:59], v63 offset0:16 offset1:84
	s_waitcnt lgkmcnt(0)
	v_fma_f32 v58, v61, v56, v58
	v_mul_f32_e32 v56, v60, v56
	v_add_u32_e32 v61, 0x9200, v149
	v_fmac_f32_e32 v59, v58, v57
	ds_write2_b32 v61, v60, v56 offset0:76 offset1:144
	ds_write2_b32 v63, v58, v59 offset0:16 offset1:84
	v_mul_f32_e32 v64, v56, v57
	ds_read2_b32 v[56:57], v62 offset0:152 offset1:220
	ds_read2_b32 v[60:61], v63 offset0:152 offset1:220
	s_waitcnt lgkmcnt(0)
	v_fma_f32 v58, v59, v56, v60
	v_mul_f32_e32 v56, v64, v56
	v_fmac_f32_e32 v61, v58, v57
	ds_write2_b32 v62, v64, v56 offset0:84 offset1:152
	ds_write2_b32 v63, v58, v61 offset0:152 offset1:220
	v_add_u32_e32 v62, 0x9800, v149
	v_add_u32_e32 v63, 0x800, v150
	v_mul_f32_e32 v60, v56, v57
	ds_read2_b32 v[56:57], v62 offset0:32 offset1:100
	ds_read2_b32 v[58:59], v63 offset0:32 offset1:100
	s_waitcnt lgkmcnt(0)
	v_fma_f32 v58, v61, v56, v58
	v_mul_f32_e32 v56, v60, v56
	v_add_u32_e32 v61, 0x9600, v149
	v_fmac_f32_e32 v59, v58, v57
	ds_write2_b32 v61, v60, v56 offset0:92 offset1:160
	ds_write2_b32 v63, v58, v59 offset0:32 offset1:100
	v_mul_f32_e32 v64, v56, v57
	ds_read2_b32 v[56:57], v62 offset0:168 offset1:236
	ds_read2_b32 v[60:61], v63 offset0:168 offset1:236
	s_waitcnt lgkmcnt(0)
	v_fma_f32 v58, v59, v56, v60
	v_mul_f32_e32 v56, v64, v56
	v_fmac_f32_e32 v61, v58, v57
	ds_write2_b32 v62, v64, v56 offset0:100 offset1:168
	ds_write2_b32 v63, v58, v61 offset0:168 offset1:236
	v_add_u32_e32 v62, 0x9c00, v149
	v_add_u32_e32 v63, 0xc00, v150
	v_mul_f32_e32 v60, v56, v57
	ds_read2_b32 v[56:57], v62 offset0:48 offset1:116
	ds_read2_b32 v[58:59], v63 offset0:48 offset1:116
	s_waitcnt lgkmcnt(0)
	v_fma_f32 v58, v61, v56, v58
	v_mul_f32_e32 v56, v60, v56
	v_add_u32_e32 v61, 0x9a00, v149
	v_fmac_f32_e32 v59, v58, v57
	ds_write2_b32 v61, v60, v56 offset0:108 offset1:176
	ds_write2_b32 v63, v58, v59 offset0:48 offset1:116
	v_mul_f32_e32 v60, v56, v57
	ds_read2_b32 v[56:57], v62 offset0:184 offset1:252
	ds_read2_b32 v[110:111], v63 offset0:184 offset1:252
	s_waitcnt lgkmcnt(0)
	v_fma_f32 v58, v59, v56, v110
	v_mul_f32_e32 v56, v60, v56
	v_fmac_f32_e32 v111, v58, v57
	ds_write2_b32 v62, v60, v56 offset0:116 offset1:184
	v_mul_f32_e32 v164, v56, v57
	ds_write2_b32 v63, v58, v111 offset0:184 offset1:252
	ds_write_b32 v149, v164 offset:40944
	ds_write_b32 v135, v164
	ds_write_b32 v136, v111
	s_waitcnt lgkmcnt(0)
	s_barrier
	v_lshl_add_u32 v56, s0, 2, v129
	ds_read_b32 v110, v56
	v_mov_b32_e32 v56, v141
	s_cbranch_vccnz .LBB0_1096
